# phase-merged K-loops extended to out-proj and down-proj GEMMs (all six standard instances)
# speedup vs baseline: 1.0263x; 1.0035x over previous
.LBB0_107:
	v_lshl_add_u64 v[10:11], s[30:31], 0, v[0:1]
	v_mov_b32_e32 v159, v1
	v_lshl_add_u64 v[12:13], s[30:31], 0, v[158:159]
	v_mov_b32_e32 v179, v1
	s_add_i32 m0, s21, 0x18000
	v_lshl_add_u64 v[10:11], v[10:11], 0, s[12:13]
	v_lshl_add_u64 v[14:15], s[36:37], 0, v[178:179]
	v_mov_b32_e32 v161, v1
	s_waitcnt vmcnt(2)
	s_barrier
	global_load_lds_dwordx4 v[10:11], off
	v_lshl_add_u64 v[10:11], v[12:13], 0, s[12:13]
	s_add_i32 m0, s21, 0x1a000
	s_add_i32 s65, s21, 0x8000
	v_lshl_add_u64 v[16:17], s[36:37], 0, v[160:161]
	global_load_lds_dwordx4 v[10:11], off
	v_lshl_add_u64 v[10:11], v[14:15], 0, s[12:13]
	s_mov_b32 m0, s65
	s_add_i32 s66, s21, 0xa000
	v_lshl_add_u64 v[18:19], s[26:27], 0, v[0:1]
	global_load_lds_dwordx4 v[10:11], off
	v_lshl_add_u64 v[10:11], v[16:17], 0, s[12:13]
	s_mov_b32 m0, s66
	v_lshl_add_u64 v[20:21], s[26:27], 0, v[158:159]
	global_load_lds_dwordx4 v[10:11], off
	s_add_i32 m0, s21, 0x1c000
	v_lshl_add_u64 v[10:11], v[18:19], 0, s[12:13]
	global_load_lds_dwordx4 v[10:11], off
	v_lshl_add_u64 v[10:11], v[20:21], 0, s[12:13]
	s_add_i32 m0, s21, 0x1e000
	v_bfe_u32 v9, v2, 4, 2
	global_load_lds_dwordx4 v[10:11], off
	v_and_b32_e32 v10, 15, v2
	v_lshlrev_b32_e32 v12, 4, v9
	v_lshlrev_b32_e32 v2, 2, v2
	s_and_b32 s67, s22, 3
	v_lshl_or_b32 v202, s4, 6, v10
	v_lshl_or_b32 v10, v10, 6, v12
	s_lshl_b32 s1, s4, 13
	v_and_b32_e32 v2, 32, v2
	v_bitop3_b32 v12, v10, s1, v2 bitop3:0xde
	s_lshl_b32 s1, s67, 12
	v_bitop3_b32 v203, v10, s1, v2 bitop3:0xde
	v_add_u32_e32 v2, v8, v6
	s_waitcnt vmcnt(6)
	v_add_lshl_u32 v6, v2, v7, 1
	v_add_u32_e32 v2, v5, v3
	s_lshr_b32 s68, s0, 6
	v_lshlrev_b32_e32 v11, 3, v9
	v_mov_b32_e32 v7, v1
	v_add_lshl_u32 v2, v2, v4, 1
	v_mov_b32_e32 v3, v1
	v_readlane_b32 s22, v253, 35
	v_lshl_or_b32 v204, s67, 5, v11
	s_add_i32 s69, s68, -2
	s_mov_b32 s70, 0
	v_cmp_eq_u32_e64 s[42:43], 0, v9
	v_lshl_add_u64 v[180:181], s[6:7], 0, v[6:7]
	v_lshl_add_u64 v[182:183], s[6:7], 0, v[2:3]
	v_add_u32_e32 v205, 0, v12
	v_readlane_b32 s4, v253, 3
	s_mov_b32 s72, s22
	s_barrier
	v_readlane_b32 s23, v253, 36
	s_branch .LBB0_109

.LBB0_120:
	s_add_i32 s23, s22, 2
	s_add_u32 s1, s36, 0x80
	s_addc_u32 s30, s37, 0
	s_add_i32 s33, 0, 0x10000
	v_add_u32_e32 v142, s33, v203
	ds_read_b128 v[130:133], v142
	ds_read_b128 v[134:137], v142 offset:1024
	ds_read_b128 v[138:141], v142 offset:2048
	ds_read_b128 v[142:145], v142 offset:3072
	s_cmp_eq_u32 s69, s22
	s_cselect_b32 s31, s27, s30
	s_cselect_b32 s30, s26, s1
	s_cselect_b32 s47, s29, s49
	s_cselect_b32 s46, s28, s48
	v_lshl_add_u64 v[176:177], s[36:37], 0, v[180:181]
	s_add_i32 m0, s21, 0xc000
	ds_read_b128 v[146:149], v205
	ds_read_b128 v[150:153], v205 offset:1024
	ds_read_b128 v[154:157], v205 offset:2048
	ds_read_b128 v[184:187], v205 offset:3072
	ds_read_b128 v[188:191], v205 offset:4096
	ds_read_b128 v[192:195], v205 offset:5120
	ds_read_b128 v[196:199], v205 offset:6144
	ds_read_b128 v[206:209], v205 offset:7168
	global_load_lds_dwordx4 v[176:177], off
	v_lshl_add_u64 v[176:177], s[36:37], 0, v[182:183]
	s_add_i32 m0, s21, 0xe000
	s_nop 0
	global_load_lds_dwordx4 v[176:177], off
	s_add_i32 s1, 0, 0x14000
	v_add_u32_e32 v168, s1, v203
	ds_read_b128 v[216:219], v168
	ds_read_b128 v[230:233], v168 offset:1024
	ds_read_b128 v[234:237], v168 offset:2048
	ds_read_b128 v[238:241], v168 offset:3072
	s_waitcnt vmcnt(8)
	s_waitcnt lgkmcnt(0)
	s_barrier
	s_setprio 1
	v_mfma_f32_16x16x32_bf16 v[126:129], v[130:133], v[146:149], v[126:129]
	v_mfma_f32_16x16x32_bf16 v[122:125], v[138:141], v[146:149], v[122:125]
	v_mfma_f32_16x16x32_bf16 v[110:113], v[130:133], v[154:157], v[110:113]
	v_mfma_f32_16x16x32_bf16 v[106:109], v[138:141], v[154:157], v[106:109]
	v_mfma_f32_16x16x32_bf16 v[94:97], v[130:133], v[188:191], v[94:97]
	v_mfma_f32_16x16x32_bf16 v[90:93], v[138:141], v[188:191], v[90:93]
	v_mfma_f32_16x16x32_bf16 v[78:81], v[130:133], v[196:199], v[78:81]
	v_mfma_f32_16x16x32_bf16 v[74:77], v[138:141], v[196:199], v[74:77]
	v_mfma_f32_16x16x32_bf16 v[126:129], v[134:137], v[150:153], v[126:129]
	v_mfma_f32_16x16x32_bf16 v[122:125], v[142:145], v[150:153], v[122:125]
	v_mfma_f32_16x16x32_bf16 v[110:113], v[134:137], v[184:187], v[110:113]
	v_mfma_f32_16x16x32_bf16 v[106:109], v[142:145], v[184:187], v[106:109]
	v_mfma_f32_16x16x32_bf16 v[94:97], v[134:137], v[192:195], v[94:97]
	v_mfma_f32_16x16x32_bf16 v[90:93], v[142:145], v[192:195], v[90:93]
	v_mfma_f32_16x16x32_bf16 v[78:81], v[134:137], v[206:209], v[78:81]
	v_mfma_f32_16x16x32_bf16 v[74:77], v[142:145], v[206:209], v[74:77]
	v_mfma_f32_16x16x32_bf16 v[118:121], v[216:219], v[146:149], v[118:121]
	v_mfma_f32_16x16x32_bf16 v[114:117], v[234:237], v[146:149], v[114:117]
	v_mfma_f32_16x16x32_bf16 v[102:105], v[216:219], v[154:157], v[102:105]
	v_mfma_f32_16x16x32_bf16 v[98:101], v[234:237], v[154:157], v[98:101]
	v_mfma_f32_16x16x32_bf16 v[86:89], v[216:219], v[188:191], v[86:89]
	v_mfma_f32_16x16x32_bf16 v[82:85], v[234:237], v[188:191], v[82:85]
	v_mfma_f32_16x16x32_bf16 v[70:73], v[216:219], v[196:199], v[70:73]
	v_mfma_f32_16x16x32_bf16 v[66:69], v[234:237], v[196:199], v[66:69]
	v_mfma_f32_16x16x32_bf16 v[118:121], v[230:233], v[150:153], v[118:121]
	v_mfma_f32_16x16x32_bf16 v[114:117], v[238:241], v[150:153], v[114:117]
	v_mfma_f32_16x16x32_bf16 v[102:105], v[230:233], v[184:187], v[102:105]
	v_mfma_f32_16x16x32_bf16 v[98:101], v[238:241], v[184:187], v[98:101]
	v_mfma_f32_16x16x32_bf16 v[86:89], v[230:233], v[192:195], v[86:89]
	v_mfma_f32_16x16x32_bf16 v[82:85], v[238:241], v[192:195], v[82:85]
	v_mfma_f32_16x16x32_bf16 v[70:73], v[230:233], v[206:209], v[70:73]
	v_mfma_f32_16x16x32_bf16 v[66:69], v[238:241], v[206:209], v[66:69]
	s_setprio 0
	s_barrier
	ds_read_b128 v[146:149], v205 offset:16384
	ds_read_b128 v[150:153], v205 offset:17408
	ds_read_b128 v[154:157], v205 offset:18432
	ds_read_b128 v[184:187], v205 offset:19456
	ds_read_b128 v[188:191], v205 offset:20480
	ds_read_b128 v[192:195], v205 offset:21504
	ds_read_b128 v[196:199], v205 offset:22528
	ds_read_b128 v[206:209], v205 offset:23552
	s_add_i32 s22, s33, s20
	v_lshl_add_u64 v[176:177], s[46:47], 0, v[0:1]
	s_mov_b32 m0, s22
	s_nop 0
	global_load_lds_dwordx4 v[176:177], off
	v_lshl_add_u64 v[200:201], s[46:47], 0, v[158:159]
	s_add_i32 m0, s22, 0x2000
	s_nop 0
	global_load_lds_dwordx4 v[200:201], off
	s_mov_b32 m0, s21
	v_lshl_add_u64 v[220:221], s[30:31], 0, v[178:179]
	global_load_lds_dwordx4 v[220:221], off
	v_lshl_add_u64 v[242:243], s[30:31], 0, v[160:161]
	s_mov_b32 m0, s34
	s_nop 0
	global_load_lds_dwordx4 v[242:243], off
	s_add_u32 s46, s46, s6
	s_addc_u32 s47, s47, 0
	s_add_i32 s1, s1, s20
	v_lshl_add_u64 v[244:245], s[46:47], 0, v[0:1]
	s_mov_b32 m0, s1
	v_lshl_add_u64 v[246:247], s[46:47], 0, v[158:159]
	global_load_lds_dwordx4 v[244:245], off
	s_add_i32 m0, s1, 0x2000
	s_nop 0
	global_load_lds_dwordx4 v[246:247], off
	s_waitcnt vmcnt(8)
	s_waitcnt lgkmcnt(0)
	s_barrier
	s_setprio 1
	v_mfma_f32_16x16x32_bf16 v[62:65], v[130:133], v[146:149], v[62:65]
	v_mfma_f32_16x16x32_bf16 v[58:61], v[138:141], v[146:149], v[58:61]
	v_mfma_f32_16x16x32_bf16 v[46:49], v[130:133], v[154:157], v[46:49]
	v_mfma_f32_16x16x32_bf16 v[42:45], v[138:141], v[154:157], v[42:45]
	v_mfma_f32_16x16x32_bf16 v[30:33], v[130:133], v[188:191], v[30:33]
	v_mfma_f32_16x16x32_bf16 v[26:29], v[138:141], v[188:191], v[26:29]
	v_mfma_f32_16x16x32_bf16 v[14:17], v[130:133], v[196:199], v[14:17]
	v_mfma_f32_16x16x32_bf16 v[10:13], v[138:141], v[196:199], v[10:13]
	v_mfma_f32_16x16x32_bf16 v[62:65], v[134:137], v[150:153], v[62:65]
	v_mfma_f32_16x16x32_bf16 v[58:61], v[142:145], v[150:153], v[58:61]
	v_mfma_f32_16x16x32_bf16 v[46:49], v[134:137], v[184:187], v[46:49]
	v_mfma_f32_16x16x32_bf16 v[42:45], v[142:145], v[184:187], v[42:45]
	v_mfma_f32_16x16x32_bf16 v[30:33], v[134:137], v[192:195], v[30:33]
	v_mfma_f32_16x16x32_bf16 v[26:29], v[142:145], v[192:195], v[26:29]
	v_mfma_f32_16x16x32_bf16 v[14:17], v[134:137], v[206:209], v[14:17]
	v_mfma_f32_16x16x32_bf16 v[10:13], v[142:145], v[206:209], v[10:13]
	v_mfma_f32_16x16x32_bf16 v[54:57], v[216:219], v[146:149], v[54:57]
	v_mfma_f32_16x16x32_bf16 v[50:53], v[234:237], v[146:149], v[50:53]
	v_mfma_f32_16x16x32_bf16 v[38:41], v[216:219], v[154:157], v[38:41]
	v_mfma_f32_16x16x32_bf16 v[34:37], v[234:237], v[154:157], v[34:37]
	v_mfma_f32_16x16x32_bf16 v[22:25], v[216:219], v[188:191], v[22:25]
	v_mfma_f32_16x16x32_bf16 v[18:21], v[234:237], v[188:191], v[18:21]
	v_mfma_f32_16x16x32_bf16 v[6:9], v[216:219], v[196:199], v[6:9]
	v_mfma_f32_16x16x32_bf16 v[2:5], v[234:237], v[196:199], v[2:5]
	v_mfma_f32_16x16x32_bf16 v[54:57], v[230:233], v[150:153], v[54:57]
	v_mfma_f32_16x16x32_bf16 v[50:53], v[238:241], v[150:153], v[50:53]
	v_mfma_f32_16x16x32_bf16 v[38:41], v[230:233], v[184:187], v[38:41]
	v_mfma_f32_16x16x32_bf16 v[34:37], v[238:241], v[184:187], v[34:37]
	v_mfma_f32_16x16x32_bf16 v[22:25], v[230:233], v[192:195], v[22:25]
	v_mfma_f32_16x16x32_bf16 v[18:21], v[238:241], v[192:195], v[18:21]
	v_mfma_f32_16x16x32_bf16 v[6:9], v[230:233], v[206:209], v[6:9]
	v_mfma_f32_16x16x32_bf16 v[2:5], v[238:241], v[206:209], v[2:5]
	s_setprio 0
	s_barrier
	s_add_i32 s1, 0, 0x18000
	v_add_u32_e32 v142, s1, v203
	ds_read_b128 v[130:133], v142
	ds_read_b128 v[134:137], v142 offset:1024
	ds_read_b128 v[138:141], v142 offset:2048
	ds_read_b128 v[142:145], v142 offset:3072
	s_add_u32 s30, s30, s6
	s_addc_u32 s31, s31, 0
	s_mov_b32 m0, s63
	v_lshl_add_u64 v[216:217], s[30:31], 0, v[178:179]
	ds_read_b128 v[146:149], v205 offset:32768
	ds_read_b128 v[150:153], v205 offset:33792
	ds_read_b128 v[154:157], v205 offset:34816
	ds_read_b128 v[184:187], v205 offset:35840
	ds_read_b128 v[188:191], v205 offset:36864
	ds_read_b128 v[192:195], v205 offset:37888
	ds_read_b128 v[196:199], v205 offset:38912
	ds_read_b128 v[206:209], v205 offset:39936
	global_load_lds_dwordx4 v[216:217], off
	v_lshl_add_u64 v[216:217], s[30:31], 0, v[160:161]
	s_mov_b32 m0, s64
	s_nop 0
	global_load_lds_dwordx4 v[216:217], off
	s_add_i32 s22, 0, 0x1c000
	v_add_u32_e32 v168, s22, v203
	ds_read_b128 v[216:219], v168
	ds_read_b128 v[230:233], v168 offset:1024
	ds_read_b128 v[234:237], v168 offset:2048
	ds_read_b128 v[238:241], v168 offset:3072
	s_waitcnt vmcnt(8)
	s_waitcnt lgkmcnt(0)
	s_barrier
	s_setprio 1
	v_mfma_f32_16x16x32_bf16 v[126:129], v[130:133], v[146:149], v[126:129]
	v_mfma_f32_16x16x32_bf16 v[122:125], v[138:141], v[146:149], v[122:125]
	v_mfma_f32_16x16x32_bf16 v[110:113], v[130:133], v[154:157], v[110:113]
	v_mfma_f32_16x16x32_bf16 v[106:109], v[138:141], v[154:157], v[106:109]
	v_mfma_f32_16x16x32_bf16 v[94:97], v[130:133], v[188:191], v[94:97]
	v_mfma_f32_16x16x32_bf16 v[90:93], v[138:141], v[188:191], v[90:93]
	v_mfma_f32_16x16x32_bf16 v[78:81], v[130:133], v[196:199], v[78:81]
	v_mfma_f32_16x16x32_bf16 v[74:77], v[138:141], v[196:199], v[74:77]
	v_mfma_f32_16x16x32_bf16 v[126:129], v[134:137], v[150:153], v[126:129]
	v_mfma_f32_16x16x32_bf16 v[122:125], v[142:145], v[150:153], v[122:125]
	v_mfma_f32_16x16x32_bf16 v[110:113], v[134:137], v[184:187], v[110:113]
	v_mfma_f32_16x16x32_bf16 v[106:109], v[142:145], v[184:187], v[106:109]
	v_mfma_f32_16x16x32_bf16 v[94:97], v[134:137], v[192:195], v[94:97]
	v_mfma_f32_16x16x32_bf16 v[90:93], v[142:145], v[192:195], v[90:93]
	v_mfma_f32_16x16x32_bf16 v[78:81], v[134:137], v[206:209], v[78:81]
	v_mfma_f32_16x16x32_bf16 v[74:77], v[142:145], v[206:209], v[74:77]
	v_mfma_f32_16x16x32_bf16 v[118:121], v[216:219], v[146:149], v[118:121]
	v_mfma_f32_16x16x32_bf16 v[114:117], v[234:237], v[146:149], v[114:117]
	v_mfma_f32_16x16x32_bf16 v[102:105], v[216:219], v[154:157], v[102:105]
	v_mfma_f32_16x16x32_bf16 v[98:101], v[234:237], v[154:157], v[98:101]
	v_mfma_f32_16x16x32_bf16 v[86:89], v[216:219], v[188:191], v[86:89]
	v_mfma_f32_16x16x32_bf16 v[82:85], v[234:237], v[188:191], v[82:85]
	v_mfma_f32_16x16x32_bf16 v[70:73], v[216:219], v[196:199], v[70:73]
	v_mfma_f32_16x16x32_bf16 v[66:69], v[234:237], v[196:199], v[66:69]
	v_mfma_f32_16x16x32_bf16 v[118:121], v[230:233], v[150:153], v[118:121]
	v_mfma_f32_16x16x32_bf16 v[114:117], v[238:241], v[150:153], v[114:117]
	v_mfma_f32_16x16x32_bf16 v[102:105], v[230:233], v[184:187], v[102:105]
	v_mfma_f32_16x16x32_bf16 v[98:101], v[238:241], v[184:187], v[98:101]
	v_mfma_f32_16x16x32_bf16 v[86:89], v[230:233], v[192:195], v[86:89]
	v_mfma_f32_16x16x32_bf16 v[82:85], v[238:241], v[192:195], v[82:85]
	v_mfma_f32_16x16x32_bf16 v[70:73], v[230:233], v[206:209], v[70:73]
	v_mfma_f32_16x16x32_bf16 v[66:69], v[238:241], v[206:209], v[66:69]
	s_setprio 0
	s_barrier
	ds_read_b128 v[146:149], v205 offset:49152
	ds_read_b128 v[150:153], v205 offset:50176
	ds_read_b128 v[154:157], v205 offset:51200
	ds_read_b128 v[184:187], v205 offset:52224
	ds_read_b128 v[188:191], v205 offset:53248
	ds_read_b128 v[192:195], v205 offset:54272
	ds_read_b128 v[196:199], v205 offset:55296
	ds_read_b128 v[206:209], v205 offset:56320
	s_add_i32 s1, s1, s20
	v_lshl_add_u64 v[176:177], v[176:177], 0, s[12:13]
	s_mov_b32 m0, s1
	s_nop 0
	global_load_lds_dwordx4 v[176:177], off
	v_lshl_add_u64 v[176:177], v[200:201], 0, s[12:13]
	s_add_i32 m0, s1, 0x2000
	s_nop 0
	global_load_lds_dwordx4 v[176:177], off
	s_mov_b32 m0, s65
	v_lshl_add_u64 v[176:177], v[220:221], 0, s[12:13]
	global_load_lds_dwordx4 v[176:177], off
	v_lshl_add_u64 v[176:177], v[242:243], 0, s[12:13]
	s_mov_b32 m0, s66
	s_nop 0
	global_load_lds_dwordx4 v[176:177], off
	s_add_i32 s1, s22, s20
	v_lshl_add_u64 v[176:177], v[244:245], 0, s[12:13]
	s_mov_b32 m0, s1
	s_nop 0
	global_load_lds_dwordx4 v[176:177], off
	v_lshl_add_u64 v[176:177], v[246:247], 0, s[12:13]
	s_add_i32 m0, s1, 0x2000
	s_nop 0
	global_load_lds_dwordx4 v[176:177], off
	s_waitcnt vmcnt(8)
	s_waitcnt lgkmcnt(0)
	s_barrier
	s_setprio 1
	v_mfma_f32_16x16x32_bf16 v[62:65], v[130:133], v[146:149], v[62:65]
	v_mfma_f32_16x16x32_bf16 v[58:61], v[138:141], v[146:149], v[58:61]
	v_mfma_f32_16x16x32_bf16 v[46:49], v[130:133], v[154:157], v[46:49]
	v_mfma_f32_16x16x32_bf16 v[42:45], v[138:141], v[154:157], v[42:45]
	v_mfma_f32_16x16x32_bf16 v[30:33], v[130:133], v[188:191], v[30:33]
	v_mfma_f32_16x16x32_bf16 v[26:29], v[138:141], v[188:191], v[26:29]
	v_mfma_f32_16x16x32_bf16 v[14:17], v[130:133], v[196:199], v[14:17]
	v_mfma_f32_16x16x32_bf16 v[10:13], v[138:141], v[196:199], v[10:13]
	v_mfma_f32_16x16x32_bf16 v[62:65], v[134:137], v[150:153], v[62:65]
	v_mfma_f32_16x16x32_bf16 v[58:61], v[142:145], v[150:153], v[58:61]
	v_mfma_f32_16x16x32_bf16 v[46:49], v[134:137], v[184:187], v[46:49]
	v_mfma_f32_16x16x32_bf16 v[42:45], v[142:145], v[184:187], v[42:45]
	v_mfma_f32_16x16x32_bf16 v[30:33], v[134:137], v[192:195], v[30:33]
	v_mfma_f32_16x16x32_bf16 v[26:29], v[142:145], v[192:195], v[26:29]
	v_mfma_f32_16x16x32_bf16 v[14:17], v[134:137], v[206:209], v[14:17]
	v_mfma_f32_16x16x32_bf16 v[10:13], v[142:145], v[206:209], v[10:13]
	v_mfma_f32_16x16x32_bf16 v[54:57], v[216:219], v[146:149], v[54:57]
	v_mfma_f32_16x16x32_bf16 v[50:53], v[234:237], v[146:149], v[50:53]
	v_mfma_f32_16x16x32_bf16 v[38:41], v[216:219], v[154:157], v[38:41]
	v_mfma_f32_16x16x32_bf16 v[34:37], v[234:237], v[154:157], v[34:37]
	v_mfma_f32_16x16x32_bf16 v[22:25], v[216:219], v[188:191], v[22:25]
	v_mfma_f32_16x16x32_bf16 v[18:21], v[234:237], v[188:191], v[18:21]
	v_mfma_f32_16x16x32_bf16 v[6:9], v[216:219], v[196:199], v[6:9]
	v_mfma_f32_16x16x32_bf16 v[2:5], v[234:237], v[196:199], v[2:5]
	v_mfma_f32_16x16x32_bf16 v[54:57], v[230:233], v[150:153], v[54:57]
	v_mfma_f32_16x16x32_bf16 v[50:53], v[238:241], v[150:153], v[50:53]
	v_mfma_f32_16x16x32_bf16 v[38:41], v[230:233], v[184:187], v[38:41]
	v_mfma_f32_16x16x32_bf16 v[34:37], v[238:241], v[184:187], v[34:37]
	v_mfma_f32_16x16x32_bf16 v[22:25], v[230:233], v[192:195], v[22:25]
	v_mfma_f32_16x16x32_bf16 v[18:21], v[238:241], v[192:195], v[18:21]
	v_mfma_f32_16x16x32_bf16 v[6:9], v[230:233], v[206:209], v[6:9]
	v_mfma_f32_16x16x32_bf16 v[2:5], v[238:241], v[206:209], v[2:5]
	s_setprio 0
	s_add_u32 s36, s36, 0x100
	s_addc_u32 s37, s37, 0
	s_add_u32 s48, s48, 0x100
	s_addc_u32 s49, s49, 0
	s_cmp_ge_u32 s23, s68
	s_mov_b32 s22, s23
	s_barrier
	s_cbranch_scc0 .LBB0_120
	v_and_b32_e32 v131, 64, v212
	v_xor_b32_e32 v130, 16, v212
	v_add_u32_e32 v131, 64, v131
	v_cmp_lt_i32_e32 vcc, v130, v131
	v_lshl_or_b32 v184, s4, 8, v204
	v_lshl_add_u32 v186, s72, 8, v202
	v_cndmask_b32_e32 v130, v212, v130, vcc
	v_ashrrev_i32_e32 v185, 31, v184
	v_lshlrev_b32_e32 v206, 2, v130
	v_xor_b32_e32 v130, 32, v212
	v_cmp_lt_i32_e32 vcc, v130, v131
	v_lshlrev_b64 v[176:177], 1, v[184:185]
	v_ashrrev_i32_e32 v187, 31, v186
	v_cndmask_b32_e32 v130, v212, v130, vcc
	v_lshl_add_u64 v[188:189], s[96:97], 0, v[176:177]
	v_lshlrev_b64 v[208:209], 11, v[186:187]
	v_lshlrev_b32_e32 v207, 2, v130
	v_lshl_add_u64 v[130:131], v[188:189], 0, v[208:209]
	global_load_dwordx4 v[216:219], v[130:131], off
	global_load_dwordx4 v[154:157], v[130:131], off offset:256
	v_or_b32_e32 v198, 16, v186
	v_ashrrev_i32_e32 v199, 31, v198
	v_or_b32_e32 v194, 32, v186
	v_lshlrev_b64 v[200:201], 11, v[198:199]
	v_ashrrev_i32_e32 v195, 31, v194
	v_or_b32_e32 v190, 48, v186
	v_lshl_add_u64 v[130:131], v[188:189], 0, v[200:201]
	v_lshlrev_b64 v[196:197], 11, v[194:195]
	v_ashrrev_i32_e32 v191, 31, v190
	global_load_dwordx4 v[150:153], v[130:131], off
	global_load_dwordx4 v[146:149], v[130:131], off offset:256
	v_lshl_add_u64 v[130:131], v[188:189], 0, v[196:197]
	v_lshlrev_b64 v[192:193], 11, v[190:191]
	global_load_dwordx4 v[142:145], v[130:131], off
	global_load_dwordx4 v[134:137], v[130:131], off offset:256
	v_lshl_add_u64 v[130:131], v[188:189], 0, v[192:193]
	global_load_dwordx4 v[138:141], v[130:131], off
	s_nop 0
	global_load_dwordx4 v[130:133], v[130:131], off offset:256
	s_lshl_b32 s36, s4, 2
	s_ashr_i32 s37, s36, 31
	s_waitcnt vmcnt(0)
	v_lshlrev_b32_e32 v220, 16, v216
	v_and_b32_e32 v221, 0xffff0000, v216
	v_lshlrev_b32_e32 v216, 16, v217
	v_and_b32_e32 v217, 0xffff0000, v217
	v_pk_add_f32 v[128:129], v[128:129], v[216:217]
	v_pk_add_f32 v[126:127], v[126:127], v[220:221]
	v_lshlrev_b32_e32 v216, 16, v218
	v_and_b32_e32 v217, 0xffff0000, v218
	v_lshlrev_b32_e32 v218, 16, v219
	v_and_b32_e32 v219, 0xffff0000, v219
	v_pk_add_f32 v[218:219], v[124:125], v[218:219]
	v_pk_add_f32 v[124:125], v[122:123], v[216:217]
	v_cvt_pk_bf16_f32 v122, v126, v127
	v_lshl_add_u64 v[126:127], s[96:97], 0, v[208:209]
	v_cvt_pk_bf16_f32 v123, v128, v129
	v_cvt_pk_bf16_f32 v124, v124, v125
	v_cvt_pk_bf16_f32 v125, v218, v219
	v_lshl_add_u64 v[126:127], v[126:127], 0, v[176:177]
	global_store_dwordx4 v[126:127], v[122:125], off
	v_lshlrev_b32_e32 v128, 16, v122
	s_nop 0
	v_and_b32_e32 v122, 0xffff0000, v122
	v_mul_f32_e32 v122, v122, v122
	v_fmac_f32_e32 v122, v128, v128
	v_lshlrev_b32_e32 v128, 16, v123
	v_and_b32_e32 v123, 0xffff0000, v123
	v_mul_f32_e32 v123, v123, v123
	v_fmac_f32_e32 v123, v128, v128
	v_add_f32_e32 v122, v122, v123
	v_lshlrev_b32_e32 v123, 16, v124
	v_and_b32_e32 v124, 0xffff0000, v124
	v_mul_f32_e32 v124, v124, v124
	v_fmac_f32_e32 v124, v123, v123
	v_add_f32_e32 v122, v124, v122
	v_and_b32_e32 v124, 0xffff0000, v125
	v_lshlrev_b32_e32 v123, 16, v125
	v_mul_f32_e32 v124, v124, v124
	v_fmac_f32_e32 v124, v123, v123
	v_add_f32_e32 v128, v124, v122
	v_lshlrev_b32_e32 v122, 16, v154
	v_and_b32_e32 v123, 0xffff0000, v154
	v_lshlrev_b32_e32 v124, 16, v155
	v_and_b32_e32 v125, 0xffff0000, v155
	v_pk_add_f32 v[120:121], v[120:121], v[124:125]
	v_pk_add_f32 v[118:119], v[118:119], v[122:123]
	v_lshlrev_b32_e32 v122, 16, v156
	v_and_b32_e32 v123, 0xffff0000, v156
	v_lshlrev_b32_e32 v124, 16, v157
	v_and_b32_e32 v125, 0xffff0000, v157
	v_pk_add_f32 v[124:125], v[116:117], v[124:125]
	v_pk_add_f32 v[116:117], v[114:115], v[122:123]
	v_cvt_pk_bf16_f32 v114, v118, v119
	v_cvt_pk_bf16_f32 v115, v120, v121
	v_cvt_pk_bf16_f32 v116, v116, v117
	v_cvt_pk_bf16_f32 v117, v124, v125
	global_store_dwordx4 v[126:127], v[114:117], off offset:256
	v_lshlrev_b32_e32 v118, 16, v114
	s_nop 0
	v_and_b32_e32 v114, 0xffff0000, v114
	v_mul_f32_e32 v114, v114, v114
	v_fmac_f32_e32 v114, v118, v118
	v_lshlrev_b32_e32 v118, 16, v115
	v_and_b32_e32 v115, 0xffff0000, v115
	v_mul_f32_e32 v115, v115, v115
	v_add_f32_e32 v114, v114, v128
	v_fmac_f32_e32 v115, v118, v118
	v_add_f32_e32 v114, v115, v114
	v_lshlrev_b32_e32 v115, 16, v116
	v_and_b32_e32 v116, 0xffff0000, v116
	v_mul_f32_e32 v116, v116, v116
	v_fmac_f32_e32 v116, v115, v115
	v_add_f32_e32 v114, v116, v114
	v_and_b32_e32 v116, 0xffff0000, v117
	v_lshlrev_b32_e32 v115, 16, v117
	v_mul_f32_e32 v116, v116, v116
	v_fmac_f32_e32 v116, v115, v115
	v_add_f32_e32 v114, v116, v114
	ds_bpermute_b32 v115, v206, v114
	s_waitcnt lgkmcnt(0)
	v_add_f32_e32 v114, v114, v115
	ds_bpermute_b32 v115, v207, v114
	s_and_saveexec_b64 s[30:31], s[42:43]
	s_cbranch_execz .LBB0_123
	v_lshlrev_b64 v[116:117], 6, v[186:187]
	v_lshl_add_u64 v[116:117], s[58:59], 0, v[116:117]
	v_lshl_add_u64 v[116:117], s[36:37], 2, v[116:117]
	s_lshl_b32 s4, s67, 2
	v_lshl_add_u64 v[116:117], v[116:117], 0, s[4:5]
	s_waitcnt lgkmcnt(0)
	v_add_f32_e32 v114, v114, v115
	global_store_dword v[116:117], v114, off

.LBB0_146:
	v_lshl_add_u64 v[10:11], s[30:31], 0, v[0:1]
	v_mov_b32_e32 v147, v1
	v_lshl_add_u64 v[12:13], s[30:31], 0, v[146:147]
	v_mov_b32_e32 v151, v1
	s_add_i32 m0, s21, 0x18000
	v_lshl_add_u64 v[10:11], v[10:11], 0, s[12:13]
	v_lshl_add_u64 v[14:15], s[36:37], 0, v[150:151]
	v_mov_b32_e32 v149, v1
	s_waitcnt vmcnt(2)
	s_barrier
	global_load_lds_dwordx4 v[10:11], off
	v_lshl_add_u64 v[10:11], v[12:13], 0, s[12:13]
	s_add_i32 m0, s21, 0x1a000
	s_add_i32 s65, s21, 0x8000
	v_lshl_add_u64 v[16:17], s[36:37], 0, v[148:149]
	global_load_lds_dwordx4 v[10:11], off
	v_lshl_add_u64 v[10:11], v[14:15], 0, s[12:13]
	s_mov_b32 m0, s65
	s_add_i32 s66, s21, 0xa000
	v_lshl_add_u64 v[18:19], s[26:27], 0, v[0:1]
	global_load_lds_dwordx4 v[10:11], off
	v_lshl_add_u64 v[10:11], v[16:17], 0, s[12:13]
	s_mov_b32 m0, s66
	v_lshl_add_u64 v[20:21], s[26:27], 0, v[146:147]
	global_load_lds_dwordx4 v[10:11], off
	s_add_i32 m0, s21, 0x1c000
	v_lshl_add_u64 v[10:11], v[18:19], 0, s[12:13]
	global_load_lds_dwordx4 v[10:11], off
	v_lshl_add_u64 v[10:11], v[20:21], 0, s[12:13]
	s_add_i32 m0, s21, 0x1e000
	v_bfe_u32 v9, v2, 4, 2
	global_load_lds_dwordx4 v[10:11], off
	v_and_b32_e32 v10, 15, v2
	v_lshlrev_b32_e32 v12, 4, v9
	v_lshlrev_b32_e32 v2, 2, v2
	s_and_b32 s67, s22, 3
	v_lshl_or_b32 v180, s4, 6, v10
	v_lshl_or_b32 v10, v10, 6, v12
	s_lshl_b32 s1, s4, 13
	v_and_b32_e32 v2, 32, v2
	v_bitop3_b32 v12, v10, s1, v2 bitop3:0xde
	s_lshl_b32 s1, s67, 12
	v_bitop3_b32 v181, v10, s1, v2 bitop3:0xde
	v_add_u32_e32 v2, v8, v6
	s_waitcnt vmcnt(6)
	v_add_lshl_u32 v6, v2, v7, 1
	v_add_u32_e32 v2, v5, v3
	s_lshr_b32 s0, s0, 6
	v_lshlrev_b32_e32 v11, 3, v9
	v_mov_b32_e32 v7, v1
	v_add_lshl_u32 v2, v2, v4, 1
	v_mov_b32_e32 v3, v1
	v_readlane_b32 s22, v253, 35
	v_lshl_or_b32 v182, s67, 5, v11
	s_add_i32 s68, s0, -2
	s_mov_b32 s69, 0
	v_cmp_eq_u32_e64 s[42:43], 0, v9
	v_lshl_add_u64 v[152:153], s[6:7], 0, v[6:7]
	v_lshl_add_u64 v[154:155], s[6:7], 0, v[2:3]
	v_add_u32_e32 v183, 0, v12
	v_readlane_b32 s4, v253, 3
	s_mov_b32 s71, s22
	s_barrier
	v_readlane_b32 s23, v253, 36
	s_branch .LBB0_148

.LBB0_159:
	s_add_i32 s23, s22, 2
	s_add_u32 s1, s36, 0x80
	s_addc_u32 s30, s37, 0
	s_add_i32 s33, 0, 0x10000
	v_add_u32_e32 v142, s33, v181
	ds_read_b128 v[130:133], v142
	ds_read_b128 v[134:137], v142 offset:1024
	ds_read_b128 v[138:141], v142 offset:2048
	ds_read_b128 v[142:145], v142 offset:3072
	s_cmp_eq_u32 s68, s22
	s_cselect_b32 s31, s27, s30
	s_cselect_b32 s30, s26, s1
	s_cselect_b32 s47, s29, s49
	s_cselect_b32 s46, s28, s48
	v_lshl_add_u64 v[160:161], s[36:37], 0, v[152:153]
	s_add_i32 m0, s21, 0xc000
	ds_read_b128 v[156:159], v183
	ds_read_b128 v[184:187], v183 offset:1024
	ds_read_b128 v[188:191], v183 offset:2048
	ds_read_b128 v[192:195], v183 offset:3072
	ds_read_b128 v[196:199], v183 offset:4096
	ds_read_b128 v[200:203], v183 offset:5120
	ds_read_b128 v[204:207], v183 offset:6144
	ds_read_b128 v[216:219], v183 offset:7168
	global_load_lds_dwordx4 v[160:161], off
	v_lshl_add_u64 v[160:161], s[36:37], 0, v[154:155]
	s_add_i32 m0, s21, 0xe000
	s_nop 0
	global_load_lds_dwordx4 v[160:161], off
	s_add_i32 s1, 0, 0x14000
	v_add_u32_e32 v160, s1, v181
	ds_read_b128 v[230:233], v160
	ds_read_b128 v[234:237], v160 offset:1024
	ds_read_b128 v[238:241], v160 offset:2048
	ds_read_b128 v[242:245], v160 offset:3072
	s_waitcnt vmcnt(8)
	s_waitcnt lgkmcnt(0)
	s_barrier
	s_setprio 1
	v_mfma_f32_16x16x32_bf16 v[126:129], v[130:133], v[156:159], v[126:129]
	v_mfma_f32_16x16x32_bf16 v[122:125], v[138:141], v[156:159], v[122:125]
	v_mfma_f32_16x16x32_bf16 v[110:113], v[130:133], v[188:191], v[110:113]
	v_mfma_f32_16x16x32_bf16 v[106:109], v[138:141], v[188:191], v[106:109]
	v_mfma_f32_16x16x32_bf16 v[94:97], v[130:133], v[196:199], v[94:97]
	v_mfma_f32_16x16x32_bf16 v[90:93], v[138:141], v[196:199], v[90:93]
	v_mfma_f32_16x16x32_bf16 v[78:81], v[130:133], v[204:207], v[78:81]
	v_mfma_f32_16x16x32_bf16 v[74:77], v[138:141], v[204:207], v[74:77]
	v_mfma_f32_16x16x32_bf16 v[126:129], v[134:137], v[184:187], v[126:129]
	v_mfma_f32_16x16x32_bf16 v[122:125], v[142:145], v[184:187], v[122:125]
	v_mfma_f32_16x16x32_bf16 v[110:113], v[134:137], v[192:195], v[110:113]
	v_mfma_f32_16x16x32_bf16 v[106:109], v[142:145], v[192:195], v[106:109]
	v_mfma_f32_16x16x32_bf16 v[94:97], v[134:137], v[200:203], v[94:97]
	v_mfma_f32_16x16x32_bf16 v[90:93], v[142:145], v[200:203], v[90:93]
	v_mfma_f32_16x16x32_bf16 v[78:81], v[134:137], v[216:219], v[78:81]
	v_mfma_f32_16x16x32_bf16 v[74:77], v[142:145], v[216:219], v[74:77]
	v_mfma_f32_16x16x32_bf16 v[118:121], v[230:233], v[156:159], v[118:121]
	v_mfma_f32_16x16x32_bf16 v[114:117], v[238:241], v[156:159], v[114:117]
	v_mfma_f32_16x16x32_bf16 v[102:105], v[230:233], v[188:191], v[102:105]
	v_mfma_f32_16x16x32_bf16 v[98:101], v[238:241], v[188:191], v[98:101]
	v_mfma_f32_16x16x32_bf16 v[86:89], v[230:233], v[196:199], v[86:89]
	v_mfma_f32_16x16x32_bf16 v[82:85], v[238:241], v[196:199], v[82:85]
	v_mfma_f32_16x16x32_bf16 v[70:73], v[230:233], v[204:207], v[70:73]
	v_mfma_f32_16x16x32_bf16 v[66:69], v[238:241], v[204:207], v[66:69]
	v_mfma_f32_16x16x32_bf16 v[118:121], v[234:237], v[184:187], v[118:121]
	v_mfma_f32_16x16x32_bf16 v[114:117], v[242:245], v[184:187], v[114:117]
	v_mfma_f32_16x16x32_bf16 v[102:105], v[234:237], v[192:195], v[102:105]
	v_mfma_f32_16x16x32_bf16 v[98:101], v[242:245], v[192:195], v[98:101]
	v_mfma_f32_16x16x32_bf16 v[86:89], v[234:237], v[200:203], v[86:89]
	v_mfma_f32_16x16x32_bf16 v[82:85], v[242:245], v[200:203], v[82:85]
	v_mfma_f32_16x16x32_bf16 v[70:73], v[234:237], v[216:219], v[70:73]
	v_mfma_f32_16x16x32_bf16 v[66:69], v[242:245], v[216:219], v[66:69]
	s_setprio 0
	s_barrier
	ds_read_b128 v[156:159], v183 offset:16384
	ds_read_b128 v[184:187], v183 offset:17408
	ds_read_b128 v[188:191], v183 offset:18432
	ds_read_b128 v[192:195], v183 offset:19456
	ds_read_b128 v[196:199], v183 offset:20480
	ds_read_b128 v[200:203], v183 offset:21504
	ds_read_b128 v[204:207], v183 offset:22528
	ds_read_b128 v[216:219], v183 offset:23552
	s_add_i32 s22, s33, s20
	v_lshl_add_u64 v[160:161], s[46:47], 0, v[0:1]
	s_mov_b32 m0, s22
	v_lshl_add_u64 v[176:177], s[46:47], 0, v[146:147]
	global_load_lds_dwordx4 v[160:161], off
	s_add_i32 m0, s22, 0x2000
	s_nop 0
	global_load_lds_dwordx4 v[176:177], off
	s_mov_b32 m0, s21
	v_lshl_add_u64 v[178:179], s[30:31], 0, v[150:151]
	global_load_lds_dwordx4 v[178:179], off
	v_lshl_add_u64 v[208:209], s[30:31], 0, v[148:149]
	s_mov_b32 m0, s34
	s_nop 0
	global_load_lds_dwordx4 v[208:209], off
	s_add_u32 s46, s46, s6
	s_addc_u32 s47, s47, 0
	s_add_i32 s1, s1, s20
	v_lshl_add_u64 v[220:221], s[46:47], 0, v[0:1]
	s_mov_b32 m0, s1
	v_lshl_add_u64 v[246:247], s[46:47], 0, v[146:147]
	global_load_lds_dwordx4 v[220:221], off
	s_add_i32 m0, s1, 0x2000
	s_nop 0
	global_load_lds_dwordx4 v[246:247], off
	s_waitcnt vmcnt(8)
	s_waitcnt lgkmcnt(0)
	s_barrier
	s_setprio 1
	v_mfma_f32_16x16x32_bf16 v[62:65], v[130:133], v[156:159], v[62:65]
	v_mfma_f32_16x16x32_bf16 v[58:61], v[138:141], v[156:159], v[58:61]
	v_mfma_f32_16x16x32_bf16 v[46:49], v[130:133], v[188:191], v[46:49]
	v_mfma_f32_16x16x32_bf16 v[42:45], v[138:141], v[188:191], v[42:45]
	v_mfma_f32_16x16x32_bf16 v[30:33], v[130:133], v[196:199], v[30:33]
	v_mfma_f32_16x16x32_bf16 v[26:29], v[138:141], v[196:199], v[26:29]
	v_mfma_f32_16x16x32_bf16 v[14:17], v[130:133], v[204:207], v[14:17]
	v_mfma_f32_16x16x32_bf16 v[10:13], v[138:141], v[204:207], v[10:13]
	v_mfma_f32_16x16x32_bf16 v[62:65], v[134:137], v[184:187], v[62:65]
	v_mfma_f32_16x16x32_bf16 v[58:61], v[142:145], v[184:187], v[58:61]
	v_mfma_f32_16x16x32_bf16 v[46:49], v[134:137], v[192:195], v[46:49]
	v_mfma_f32_16x16x32_bf16 v[42:45], v[142:145], v[192:195], v[42:45]
	v_mfma_f32_16x16x32_bf16 v[30:33], v[134:137], v[200:203], v[30:33]
	v_mfma_f32_16x16x32_bf16 v[26:29], v[142:145], v[200:203], v[26:29]
	v_mfma_f32_16x16x32_bf16 v[14:17], v[134:137], v[216:219], v[14:17]
	v_mfma_f32_16x16x32_bf16 v[10:13], v[142:145], v[216:219], v[10:13]
	v_mfma_f32_16x16x32_bf16 v[54:57], v[230:233], v[156:159], v[54:57]
	v_mfma_f32_16x16x32_bf16 v[50:53], v[238:241], v[156:159], v[50:53]
	v_mfma_f32_16x16x32_bf16 v[38:41], v[230:233], v[188:191], v[38:41]
	v_mfma_f32_16x16x32_bf16 v[34:37], v[238:241], v[188:191], v[34:37]
	v_mfma_f32_16x16x32_bf16 v[22:25], v[230:233], v[196:199], v[22:25]
	v_mfma_f32_16x16x32_bf16 v[18:21], v[238:241], v[196:199], v[18:21]
	v_mfma_f32_16x16x32_bf16 v[6:9], v[230:233], v[204:207], v[6:9]
	v_mfma_f32_16x16x32_bf16 v[2:5], v[238:241], v[204:207], v[2:5]
	v_mfma_f32_16x16x32_bf16 v[54:57], v[234:237], v[184:187], v[54:57]
	v_mfma_f32_16x16x32_bf16 v[50:53], v[242:245], v[184:187], v[50:53]
	v_mfma_f32_16x16x32_bf16 v[38:41], v[234:237], v[192:195], v[38:41]
	v_mfma_f32_16x16x32_bf16 v[34:37], v[242:245], v[192:195], v[34:37]
	v_mfma_f32_16x16x32_bf16 v[22:25], v[234:237], v[200:203], v[22:25]
	v_mfma_f32_16x16x32_bf16 v[18:21], v[242:245], v[200:203], v[18:21]
	v_mfma_f32_16x16x32_bf16 v[6:9], v[234:237], v[216:219], v[6:9]
	v_mfma_f32_16x16x32_bf16 v[2:5], v[242:245], v[216:219], v[2:5]
	s_setprio 0
	s_barrier
	s_add_i32 s1, 0, 0x18000
	v_add_u32_e32 v142, s1, v181
	ds_read_b128 v[130:133], v142
	ds_read_b128 v[134:137], v142 offset:1024
	ds_read_b128 v[138:141], v142 offset:2048
	ds_read_b128 v[142:145], v142 offset:3072
	s_add_u32 s30, s30, s6
	s_addc_u32 s31, s31, 0
	s_mov_b32 m0, s63
	v_lshl_add_u64 v[230:231], s[30:31], 0, v[150:151]
	ds_read_b128 v[156:159], v183 offset:32768
	ds_read_b128 v[184:187], v183 offset:33792
	ds_read_b128 v[188:191], v183 offset:34816
	ds_read_b128 v[192:195], v183 offset:35840
	ds_read_b128 v[196:199], v183 offset:36864
	ds_read_b128 v[200:203], v183 offset:37888
	ds_read_b128 v[204:207], v183 offset:38912
	ds_read_b128 v[216:219], v183 offset:39936
	global_load_lds_dwordx4 v[230:231], off
	v_lshl_add_u64 v[230:231], s[30:31], 0, v[148:149]
	s_mov_b32 m0, s64
	s_nop 0
	global_load_lds_dwordx4 v[230:231], off
	s_add_i32 s22, 0, 0x1c000
	v_add_u32_e32 v168, s22, v181
	ds_read_b128 v[230:233], v168
	ds_read_b128 v[234:237], v168 offset:1024
	ds_read_b128 v[238:241], v168 offset:2048
	ds_read_b128 v[242:245], v168 offset:3072
	s_waitcnt vmcnt(8)
	s_waitcnt lgkmcnt(0)
	s_barrier
	s_setprio 1
	v_mfma_f32_16x16x32_bf16 v[126:129], v[130:133], v[156:159], v[126:129]
	v_mfma_f32_16x16x32_bf16 v[122:125], v[138:141], v[156:159], v[122:125]
	v_mfma_f32_16x16x32_bf16 v[110:113], v[130:133], v[188:191], v[110:113]
	v_mfma_f32_16x16x32_bf16 v[106:109], v[138:141], v[188:191], v[106:109]
	v_mfma_f32_16x16x32_bf16 v[94:97], v[130:133], v[196:199], v[94:97]
	v_mfma_f32_16x16x32_bf16 v[90:93], v[138:141], v[196:199], v[90:93]
	v_mfma_f32_16x16x32_bf16 v[78:81], v[130:133], v[204:207], v[78:81]
	v_mfma_f32_16x16x32_bf16 v[74:77], v[138:141], v[204:207], v[74:77]
	v_mfma_f32_16x16x32_bf16 v[126:129], v[134:137], v[184:187], v[126:129]
	v_mfma_f32_16x16x32_bf16 v[122:125], v[142:145], v[184:187], v[122:125]
	v_mfma_f32_16x16x32_bf16 v[110:113], v[134:137], v[192:195], v[110:113]
	v_mfma_f32_16x16x32_bf16 v[106:109], v[142:145], v[192:195], v[106:109]
	v_mfma_f32_16x16x32_bf16 v[94:97], v[134:137], v[200:203], v[94:97]
	v_mfma_f32_16x16x32_bf16 v[90:93], v[142:145], v[200:203], v[90:93]
	v_mfma_f32_16x16x32_bf16 v[78:81], v[134:137], v[216:219], v[78:81]
	v_mfma_f32_16x16x32_bf16 v[74:77], v[142:145], v[216:219], v[74:77]
	v_mfma_f32_16x16x32_bf16 v[118:121], v[230:233], v[156:159], v[118:121]
	v_mfma_f32_16x16x32_bf16 v[114:117], v[238:241], v[156:159], v[114:117]
	v_mfma_f32_16x16x32_bf16 v[102:105], v[230:233], v[188:191], v[102:105]
	v_mfma_f32_16x16x32_bf16 v[98:101], v[238:241], v[188:191], v[98:101]
	v_mfma_f32_16x16x32_bf16 v[86:89], v[230:233], v[196:199], v[86:89]
	v_mfma_f32_16x16x32_bf16 v[82:85], v[238:241], v[196:199], v[82:85]
	v_mfma_f32_16x16x32_bf16 v[70:73], v[230:233], v[204:207], v[70:73]
	v_mfma_f32_16x16x32_bf16 v[66:69], v[238:241], v[204:207], v[66:69]
	v_mfma_f32_16x16x32_bf16 v[118:121], v[234:237], v[184:187], v[118:121]
	v_mfma_f32_16x16x32_bf16 v[114:117], v[242:245], v[184:187], v[114:117]
	v_mfma_f32_16x16x32_bf16 v[102:105], v[234:237], v[192:195], v[102:105]
	v_mfma_f32_16x16x32_bf16 v[98:101], v[242:245], v[192:195], v[98:101]
	v_mfma_f32_16x16x32_bf16 v[86:89], v[234:237], v[200:203], v[86:89]
	v_mfma_f32_16x16x32_bf16 v[82:85], v[242:245], v[200:203], v[82:85]
	v_mfma_f32_16x16x32_bf16 v[70:73], v[234:237], v[216:219], v[70:73]
	v_mfma_f32_16x16x32_bf16 v[66:69], v[242:245], v[216:219], v[66:69]
	s_setprio 0
	s_barrier
	ds_read_b128 v[156:159], v183 offset:49152
	ds_read_b128 v[184:187], v183 offset:50176
	ds_read_b128 v[188:191], v183 offset:51200
	ds_read_b128 v[192:195], v183 offset:52224
	ds_read_b128 v[196:199], v183 offset:53248
	ds_read_b128 v[200:203], v183 offset:54272
	ds_read_b128 v[204:207], v183 offset:55296
	ds_read_b128 v[216:219], v183 offset:56320
	s_add_i32 s1, s1, s20
	v_lshl_add_u64 v[160:161], v[160:161], 0, s[12:13]
	s_mov_b32 m0, s1
	s_nop 0
	global_load_lds_dwordx4 v[160:161], off
	v_lshl_add_u64 v[160:161], v[176:177], 0, s[12:13]
	s_add_i32 m0, s1, 0x2000
	s_nop 0
	global_load_lds_dwordx4 v[160:161], off
	s_mov_b32 m0, s65
	v_lshl_add_u64 v[160:161], v[178:179], 0, s[12:13]
	global_load_lds_dwordx4 v[160:161], off
	v_lshl_add_u64 v[160:161], v[208:209], 0, s[12:13]
	s_mov_b32 m0, s66
	s_nop 0
	global_load_lds_dwordx4 v[160:161], off
	s_add_i32 s1, s22, s20
	v_lshl_add_u64 v[160:161], v[220:221], 0, s[12:13]
	s_mov_b32 m0, s1
	s_nop 0
	global_load_lds_dwordx4 v[160:161], off
	v_lshl_add_u64 v[160:161], v[246:247], 0, s[12:13]
	s_add_i32 m0, s1, 0x2000
	s_nop 0
	global_load_lds_dwordx4 v[160:161], off
	s_waitcnt vmcnt(8)
	s_waitcnt lgkmcnt(0)
	s_barrier
	s_setprio 1
	v_mfma_f32_16x16x32_bf16 v[62:65], v[130:133], v[156:159], v[62:65]
	v_mfma_f32_16x16x32_bf16 v[58:61], v[138:141], v[156:159], v[58:61]
	v_mfma_f32_16x16x32_bf16 v[46:49], v[130:133], v[188:191], v[46:49]
	v_mfma_f32_16x16x32_bf16 v[42:45], v[138:141], v[188:191], v[42:45]
	v_mfma_f32_16x16x32_bf16 v[30:33], v[130:133], v[196:199], v[30:33]
	v_mfma_f32_16x16x32_bf16 v[26:29], v[138:141], v[196:199], v[26:29]
	v_mfma_f32_16x16x32_bf16 v[14:17], v[130:133], v[204:207], v[14:17]
	v_mfma_f32_16x16x32_bf16 v[10:13], v[138:141], v[204:207], v[10:13]
	v_mfma_f32_16x16x32_bf16 v[62:65], v[134:137], v[184:187], v[62:65]
	v_mfma_f32_16x16x32_bf16 v[58:61], v[142:145], v[184:187], v[58:61]
	v_mfma_f32_16x16x32_bf16 v[46:49], v[134:137], v[192:195], v[46:49]
	v_mfma_f32_16x16x32_bf16 v[42:45], v[142:145], v[192:195], v[42:45]
	v_mfma_f32_16x16x32_bf16 v[30:33], v[134:137], v[200:203], v[30:33]
	v_mfma_f32_16x16x32_bf16 v[26:29], v[142:145], v[200:203], v[26:29]
	v_mfma_f32_16x16x32_bf16 v[14:17], v[134:137], v[216:219], v[14:17]
	v_mfma_f32_16x16x32_bf16 v[10:13], v[142:145], v[216:219], v[10:13]
	v_mfma_f32_16x16x32_bf16 v[54:57], v[230:233], v[156:159], v[54:57]
	v_mfma_f32_16x16x32_bf16 v[50:53], v[238:241], v[156:159], v[50:53]
	v_mfma_f32_16x16x32_bf16 v[38:41], v[230:233], v[188:191], v[38:41]
	v_mfma_f32_16x16x32_bf16 v[34:37], v[238:241], v[188:191], v[34:37]
	v_mfma_f32_16x16x32_bf16 v[22:25], v[230:233], v[196:199], v[22:25]
	v_mfma_f32_16x16x32_bf16 v[18:21], v[238:241], v[196:199], v[18:21]
	v_mfma_f32_16x16x32_bf16 v[6:9], v[230:233], v[204:207], v[6:9]
	v_mfma_f32_16x16x32_bf16 v[2:5], v[238:241], v[204:207], v[2:5]
	v_mfma_f32_16x16x32_bf16 v[54:57], v[234:237], v[184:187], v[54:57]
	v_mfma_f32_16x16x32_bf16 v[50:53], v[242:245], v[184:187], v[50:53]
	v_mfma_f32_16x16x32_bf16 v[38:41], v[234:237], v[192:195], v[38:41]
	v_mfma_f32_16x16x32_bf16 v[34:37], v[242:245], v[192:195], v[34:37]
	v_mfma_f32_16x16x32_bf16 v[22:25], v[234:237], v[200:203], v[22:25]
	v_mfma_f32_16x16x32_bf16 v[18:21], v[242:245], v[200:203], v[18:21]
	v_mfma_f32_16x16x32_bf16 v[6:9], v[234:237], v[216:219], v[6:9]
	v_mfma_f32_16x16x32_bf16 v[2:5], v[242:245], v[216:219], v[2:5]
	s_setprio 0
	s_add_u32 s36, s36, 0x100
	s_addc_u32 s37, s37, 0
	s_add_u32 s48, s48, 0x100
	s_addc_u32 s49, s49, 0
	s_cmp_ge_u32 s23, s0
	s_mov_b32 s22, s23
	s_barrier
	s_cbranch_scc0 .LBB0_159
	v_readlane_b32 s22, v254, 31
	v_readlane_b32 s23, v254, 32
	s_load_dwordx2 s[22:23], s[22:23], 0x0
	v_lshl_add_u32 v158, s71, 8, v180
	v_lshl_or_b32 v156, s4, 8, v182
	v_ashrrev_i32_e32 v157, 31, v156
	v_ashrrev_i32_e32 v159, 31, v158
	s_waitcnt lgkmcnt(0)
	v_lshl_add_u64 v[160:161], v[156:157], 2, s[22:23]
	v_lshlrev_b64 v[130:131], 12, v[158:159]
	v_lshl_add_u64 v[130:131], v[160:161], 0, v[130:131]
	global_load_dwordx4 v[186:189], v[130:131], off
	global_load_dwordx4 v[190:193], v[130:131], off offset:16
	global_load_dwordx4 v[194:197], v[130:131], off offset:512
	global_load_dwordx4 v[198:201], v[130:131], off offset:528
	v_or_b32_e32 v178, 16, v158
	v_ashrrev_i32_e32 v179, 31, v178
	v_lshlrev_b64 v[130:131], 12, v[178:179]
	v_lshl_add_u64 v[134:135], v[160:161], 0, v[130:131]
	global_load_dwordx4 v[138:141], v[134:135], off offset:16
	global_load_dwordx4 v[142:145], v[134:135], off
	global_load_dwordx4 v[130:133], v[134:135], off offset:528
	s_nop 0
	global_load_dwordx4 v[134:137], v[134:135], off offset:512
	v_and_b32_e32 v169, 64, v212
	v_xor_b32_e32 v168, 16, v212
	v_add_u32_e32 v169, 64, v169
	v_xor_b32_e32 v176, 32, v212
	v_cmp_lt_i32_e32 vcc, v168, v169
	s_lshl_b32 s36, s4, 2
	s_ashr_i32 s37, s36, 31
	v_cndmask_b32_e32 v168, v212, v168, vcc
	v_cmp_lt_i32_e32 vcc, v176, v169
	v_lshlrev_b32_e32 v184, 2, v168
	s_waitcnt vmcnt(0)
	v_pk_add_f32 v[128:129], v[128:129], v[188:189]
	v_pk_add_f32 v[126:127], v[126:127], v[186:187]
	v_cndmask_b32_e32 v169, v212, v176, vcc
	v_pk_add_f32 v[122:123], v[122:123], v[190:191]
	v_pk_add_f32 v[176:177], v[120:121], v[196:197]
	v_pk_add_f32 v[116:117], v[116:117], v[200:201]
	v_pk_add_f32 v[114:115], v[114:115], v[198:199]
	v_cvt_pk_bf16_f32 v120, v126, v127
	v_cvt_pk_bf16_f32 v121, v128, v129
	v_pk_add_f32 v[124:125], v[124:125], v[192:193]
	v_pk_add_f32 v[118:119], v[118:119], v[194:195]
	v_cvt_pk_bf16_f32 v122, v122, v123
	v_cvt_pk_bf16_f32 v126, v114, v115
	v_cvt_pk_bf16_f32 v127, v116, v117
	v_and_b32_e32 v115, 0xffff0000, v120
	v_and_b32_e32 v117, 0xffff0000, v121
	v_cvt_pk_bf16_f32 v123, v124, v125
	v_cvt_pk_bf16_f32 v124, v118, v119
	v_lshlrev_b32_e32 v114, 16, v120
	v_lshlrev_b32_e32 v116, 16, v121
	v_and_b32_e32 v119, 0xffff0000, v122
	v_mul_f32_e32 v115, v115, v115
	v_mul_f32_e32 v117, v117, v117
	v_lshlrev_b32_e32 v118, 16, v122
	v_and_b32_e32 v129, 0xffff0000, v123
	v_mul_f32_e32 v119, v119, v119
	v_fmac_f32_e32 v115, v114, v114
	v_fmac_f32_e32 v117, v116, v116
	v_cvt_pk_bf16_f32 v125, v176, v177
	v_lshlrev_b32_e32 v128, 16, v123
	v_and_b32_e32 v176, 0xffff0000, v124
	v_mul_f32_e32 v129, v129, v129
	v_fmac_f32_e32 v119, v118, v118
	v_add_f32_e32 v114, v115, v117
	v_lshlrev_b32_e32 v168, 16, v124
	v_and_b32_e32 v185, 0xffff0000, v125
	v_mul_f32_e32 v176, v176, v176
	v_fmac_f32_e32 v129, v128, v128
	v_add_f32_e32 v114, v114, v119
	v_lshlrev_b32_e32 v177, 16, v125
	v_and_b32_e32 v187, 0xffff0000, v126
	v_mul_f32_e32 v185, v185, v185
	v_fmac_f32_e32 v176, v168, v168
	v_add_f32_e32 v114, v129, v114
	v_lshlrev_b32_e32 v186, 16, v126
	v_and_b32_e32 v189, 0xffff0000, v127
	v_mul_f32_e32 v187, v187, v187
	v_fmac_f32_e32 v185, v177, v177
	v_add_f32_e32 v114, v176, v114
	v_lshlrev_b32_e32 v188, 16, v127
	v_mul_f32_e32 v189, v189, v189
	v_fmac_f32_e32 v187, v186, v186
	v_add_f32_e32 v114, v185, v114
	v_add_f32_e32 v114, v187, v114
	v_fmac_f32_e32 v189, v188, v188
	v_add_f32_e32 v114, v189, v114
	ds_bpermute_b32 v115, v184, v114
	v_lshlrev_b32_e32 v118, 2, v169
	v_lshlrev_b64 v[116:117], 11, v[158:159]
	v_lshl_add_u64 v[116:117], s[96:97], 0, v[116:117]
	v_lshl_add_u64 v[116:117], v[156:157], 1, v[116:117]
	s_waitcnt lgkmcnt(0)
	v_add_f32_e32 v114, v114, v115
	ds_bpermute_b32 v115, v118, v114
	global_store_dwordx4 v[116:117], v[120:123], off
	global_store_dwordx4 v[116:117], v[124:127], off offset:256
	s_and_saveexec_b64 s[30:31], s[42:43]
	s_cbranch_execz .LBB0_162
	v_lshlrev_b64 v[116:117], 6, v[158:159]
	v_lshl_add_u64 v[116:117], s[58:59], 0, v[116:117]
	v_lshl_add_u64 v[116:117], s[36:37], 2, v[116:117]
	s_lshl_b32 s4, s67, 2
	v_lshl_add_u64 v[116:117], v[116:117], 0, s[4:5]
	s_waitcnt lgkmcnt(0)
	v_add_f32_e32 v114, v114, v115
	global_store_dword v[116:117], v114, off
